# N=2048 GEMMs (mixer out-projections and MLP down): tile groups 4x8 instead of 8x8, every A panel streamed once per XCD round
# baseline (speedup 1.0000x reference)
.LBB0_408:
	s_andn2_b64 vcc, exec, s[0:1]
	s_cbranch_vccnz .LBB0_489
	v_readlane_b32 s0, v254, 0
	v_readlane_b32 s1, v254, 1
	v_readlane_b32 s2, v254, 4
	s_mov_b32 s20, s80
	s_waitcnt vmcnt(0)
	v_mov_b64_e32 v[2:3], s[0:1]
	v_mbcnt_lo_u32_b32 v0, -1, 0
	v_mbcnt_hi_u32_b32 v0, -1, v0
	flat_load_dwordx2 v[132:133], v[2:3] offset:224
	v_mbcnt_lo_u32_b32 v0, -1, 0
	v_mbcnt_hi_u32_b32 v0, -1, v0
	s_cmpk_lt_i32 s20, 0x500
	v_add_u32_e32 v0, s81, v0
	s_cselect_b64 s[0:1], -1, 0
	s_cmpk_gt_i32 s20, 0x4ff
	v_readfirstlane_b32 s2, v0
	s_cbranch_scc1 .LBB0_411
	s_ashr_i32 s3, s20, 31
	s_lshr_b32 s3, s3, 29
	s_add_i32 s3, s20, s3
	s_ashr_i32 s6, s3, 3
	s_and_b32 s3, s3, -8
	s_sub_i32 s3, s20, s3
	s_cmp_lt_i32 s3, 0
	s_movk_i32 s7, 0xa1
	s_cselect_b32 s7, s7, 0xa0
	s_mul_i32 s3, s3, s7
	s_add_i32 s3, s3, s6
	s_ashr_i32 s6, s3, 31
	s_lshr_b32 s6, s6, 26
	s_add_i32 s6, s3, s6
	s_ashr_i32 s7, s6, 5
	s_and_b32 s6, s6, 0xffe0
	s_sub_i32 s3, s3, s6
	s_bfe_i32 s6, s3, 0x80000
	s_bfe_u32 s6, s6, 0x3000c
	s_add_i32 s6, s3, s6
	s_bfe_i32 s8, s6, 0x80000
	s_and_b32 s6, s6, 0xfc
	s_sub_i32 s3, s3, s6
	s_lshl_b32 s7, s7, 2
	s_sext_i32_i16 s8, s8
	s_sext_i32_i8 s3, s3
	s_add_i32 s16, s7, s3
	s_ashr_i32 s14, s8, 2

.LBB0_417:
	s_add_i32 s30, s30, 1
	s_mul_i32 s8, s30, s31
	s_mul_hi_u32 s9, s30, s21
	s_add_i32 s9, s9, s8
	s_mul_i32 s8, s30, s21
	s_add_u32 s18, s8, s20
	s_addc_u32 s19, s9, s34
	v_mov_b64_e32 v[132:133], 0x4ff
	v_cmp_gt_i64_e32 vcc, s[18:19], v[132:133]
	v_cmp_lt_i64_e64 s[8:9], s[18:19], v[242:243]
	s_cbranch_vccnz .LBB0_419
	s_ashr_i32 s10, s18, 31
	s_lshr_b32 s10, s10, 29
	s_add_i32 s10, s18, s10
	s_ashr_i32 s11, s10, 3
	s_and_b32 s10, s10, -8
	s_sub_i32 s10, s18, s10
	s_cmp_lt_i32 s10, 0
	s_movk_i32 s12, 0xa1
	s_cselect_b32 s12, s12, 0xa0
	s_mul_i32 s10, s10, s12
	s_add_i32 s10, s10, s11
	s_ashr_i32 s11, s10, 31
	s_lshr_b32 s11, s11, 26
	s_add_i32 s11, s10, s11
	s_ashr_i32 s12, s11, 5
	s_lshl_b32 s12, s12, 2
	s_sub_i32 s13, 0xa0, s12
	s_min_i32 s13, s13, 4
	s_abs_i32 s15, s13
	v_cvt_f32_u32_e32 v0, s15
	s_sub_i32 s18, 0, s15
	s_andn2_b32 s11, s11, 31
	s_sub_i32 s11, s10, s11
	v_rcp_iflag_f32_e32 v0, v0
	s_abs_i32 s10, s11
	s_xor_b32 s17, s11, s13
	s_ashr_i32 s17, s17, 31
	v_mul_f32_e32 v0, 0x4f7ffffe, v0
	v_cvt_u32_f32_e32 v0, v0
	s_nop 0
	v_readfirstlane_b32 s19, v0
	s_mul_i32 s18, s18, s19
	s_mul_hi_u32 s18, s19, s18
	s_add_i32 s19, s19, s18
	s_mul_hi_u32 s18, s10, s19
	s_mul_i32 s19, s18, s15
	s_sub_i32 s10, s10, s19
	s_add_i32 s35, s18, 1
	s_sub_i32 s19, s10, s15
	s_cmp_ge_u32 s10, s15
	s_cselect_b32 s18, s35, s18
	s_cselect_b32 s10, s19, s10
	s_add_i32 s19, s18, 1
	s_cmp_ge_u32 s10, s15
	s_cselect_b32 s10, s19, s18
	s_xor_b32 s10, s10, s17
	s_sub_i32 s10, s10, s17
	s_mul_i32 s13, s10, s13
	s_sub_i32 s11, s11, s13
	s_add_i32 s12, s12, s11

.LBB0_1069:
	s_andn2_b64 vcc, exec, s[0:1]
	s_cbranch_vccnz .LBB0_1152
	v_readlane_b32 s0, v254, 0
	v_readlane_b32 s1, v254, 1
	v_readlane_b32 s2, v254, 4
	s_mov_b32 s14, s80
	s_waitcnt vmcnt(0)
	v_mov_b64_e32 v[2:3], s[0:1]
	v_mbcnt_lo_u32_b32 v0, -1, 0
	v_mbcnt_hi_u32_b32 v0, -1, v0
	flat_load_dwordx2 v[134:135], v[2:3] offset:224
	v_mbcnt_lo_u32_b32 v0, -1, 0
	v_mbcnt_hi_u32_b32 v0, -1, v0
	s_cmpk_lt_i32 s14, 0x500
	v_add_u32_e32 v0, s81, v0
	s_cselect_b64 s[0:1], -1, 0
	s_cmpk_gt_i32 s14, 0x4ff
	v_readfirstlane_b32 s2, v0
	s_cbranch_scc1 .LBB0_1072
	s_ashr_i32 s3, s14, 31
	s_lshr_b32 s3, s3, 29
	s_add_i32 s3, s14, s3
	s_waitcnt lgkmcnt(0)
	s_ashr_i32 s4, s3, 3
	s_and_b32 s3, s3, -8
	s_sub_i32 s3, s14, s3
	s_cmp_lt_i32 s3, 0
	s_movk_i32 s5, 0xa1
	s_cselect_b32 s5, s5, 0xa0
	s_mul_i32 s3, s3, s5
	s_add_i32 s3, s3, s4
	s_ashr_i32 s4, s3, 31
	s_lshr_b32 s4, s4, 26
	s_add_i32 s4, s3, s4
	s_ashr_i32 s5, s4, 5
	s_and_b32 s4, s4, 0xffe0
	s_sub_i32 s3, s3, s4
	s_bfe_i32 s4, s3, 0x80000
	s_bfe_u32 s4, s4, 0x3000c
	s_add_i32 s4, s3, s4
	s_bfe_i32 s6, s4, 0x80000
	s_and_b32 s4, s4, 0xfc
	s_sub_i32 s3, s3, s4
	s_lshl_b32 s5, s5, 2
	s_sext_i32_i16 s6, s6
	s_sext_i32_i8 s3, s3
	s_add_i32 s28, s5, s3
	s_ashr_i32 s12, s6, 2

.LBB0_1078:
	s_add_i32 s24, s24, 1
	s_mul_i32 s6, s24, s25
	s_mul_hi_u32 s7, s24, s15
	s_add_i32 s7, s7, s6
	s_mul_i32 s6, s24, s15
	s_add_u32 s6, s6, s14
	s_addc_u32 s7, s7, s26
	v_mov_b64_e32 v[134:135], 0x4ff
	v_cmp_gt_i64_e32 vcc, s[6:7], v[134:135]
	v_cmp_lt_i64_e64 s[8:9], s[6:7], v[242:243]
	s_cbranch_vccnz .LBB0_1080
	s_ashr_i32 s7, s6, 31
	s_lshr_b32 s7, s7, 29
	s_add_i32 s7, s6, s7
	s_ashr_i32 s10, s7, 3
	s_and_b32 s7, s7, -8
	s_sub_i32 s6, s6, s7
	s_cmp_lt_i32 s6, 0
	s_movk_i32 s7, 0xa1
	s_cselect_b32 s7, s7, 0xa0
	s_mul_i32 s6, s6, s7
	s_add_i32 s6, s6, s10
	s_ashr_i32 s7, s6, 31
	s_lshr_b32 s7, s7, 26
	s_add_i32 s7, s6, s7
	s_ashr_i32 s10, s7, 5
	s_lshl_b32 s11, s10, 2
	s_sub_i32 s10, 0xa0, s11
	s_min_i32 s13, s10, 4
	s_abs_i32 s10, s13
	v_cvt_f32_u32_e32 v0, s10
	s_sub_i32 s29, 0, s10
	s_andn2_b32 s7, s7, 31
	s_sub_i32 s6, s6, s7
	v_rcp_iflag_f32_e32 v0, v0
	s_abs_i32 s7, s6
	s_xor_b32 s27, s6, s13
	s_ashr_i32 s27, s27, 31
	v_mul_f32_e32 v0, 0x4f7ffffe, v0
	v_cvt_u32_f32_e32 v0, v0
	s_nop 0
	v_readfirstlane_b32 s30, v0
	s_mul_i32 s29, s29, s30
	s_mul_hi_u32 s29, s30, s29
	s_add_i32 s30, s30, s29
	s_mul_hi_u32 s29, s7, s30
	s_mul_i32 s30, s29, s10
	s_sub_i32 s7, s7, s30
	s_add_i32 s31, s29, 1
	s_sub_i32 s30, s7, s10
	s_cmp_ge_u32 s7, s10
	s_cselect_b32 s29, s31, s29
	s_cselect_b32 s7, s30, s7
	s_add_i32 s30, s29, 1
	s_cmp_ge_u32 s7, s10
	s_cselect_b32 s7, s30, s29
	s_xor_b32 s7, s7, s27
	s_sub_i32 s10, s7, s27
	s_mul_i32 s7, s10, s13
	s_sub_i32 s6, s6, s7
	s_add_i32 s27, s11, s6
